# hyena depthwise conv: per channel all 16 chunk loads and 32 halo loads issued together, one wait (was 2-3 exposed round trips per chunk)
# speedup vs baseline: 1.0274x; 1.0001x over previous
; __device__ __forceinline__ float bf2f(bf16_t b) { return __uint_as_float(((unsigned)b) << 16); }
; __device__ __forceinline__ float bflo(unsigned w) { return __uint_as_float(w << 16); }
; __device__ __forceinline__ float bfhi(unsigned w) { return __uint_as_float(w & 0xffff0000u); }
; __device__ __forceinline__ void hyena_unit(const Args& a, int L, int c, LAS unsigned char* lds) {
;     ...
;         const int hc = 256 * k3 + c;
;         const float w0 = cwp[hc], w1 = cwp[768 + hc], w2 = cwp[1536 + hc], bb = cbp[hc];
;         const bf16_t* src = UT + (size_t)hc * MTOK; bf16_t* dst = UC + (size_t)hc * MTOK;
;         for (int ck = tid; ck < MTOK / 8; ck += 512) {
;             const int t0 = ck * 8, s = t0 & 2047;
;             const u32x4 v = *(const u32x4*)(src + t0);
;             float x[10];
;             x[0] = (s == 0) ? 0.f : bf2f(src[t0 - 1]);
;             x[1] = bflo(v.x); x[2] = bfhi(v.x); x[3] = bflo(v.y); x[4] = bfhi(v.y); x[5] = bflo(v.z); x[6] = bfhi(v.z); x[7] = bflo(v.w); x[8] = bfhi(v.w);
;             x[9] = (s == 2040) ? 0.f : bf2f(src[t0 + 8]);
.LBB0_163:
	s_and_saveexec_b64 s[2:3], vcc
	s_cbranch_execz .LBB0_162
	s_lshl_b32 s0, s19, 8
	s_add_i32 s0, s0, s18
	s_ashr_i32 s1, s0, 31
	s_lshl_b64 s[20:21], s[0:1], 2
	s_add_u32 s22, s35, s20
	s_addc_u32 s23, s36, s21
	s_add_u32 s20, s37, s20
	global_load_dword v4, v155, s[22:23]
	global_load_dword v7, v155, s[22:23] offset:3072
	global_load_dword v6, v228, s[22:23] offset:2048
	s_addc_u32 s21, s38, s21
	global_load_dword v18, v155, s[20:21]
	s_lshl_b64 s[0:1], s[0:1], 17
	s_add_u32 s20, s68, s0
	s_addc_u32 s21, s69, s1
	s_add_u32 s22, s66, s0
	s_addc_u32 s23, s67, s1
	s_mov_b64 s[24:25], 0
	v_mov_b32_e32 v10, v17
	v_mov_b32_e32 v19, v16
	s_waitcnt vmcnt(0)
	v_mov_b32_e32 v9, v4
	v_mov_b32_e32 v5, v6
	v_mov_b32_e32 v8, v6
	v_lshlrev_b32_e32 v26, 1, v17
	v_and_b32_e32 v27, 0x7f8, v17
	v_mov_b32_e32 v96, 0
	v_mov_b32_e32 v112, 0
	v_mov_b32_e32 v97, 0
	v_mov_b32_e32 v113, 0
	v_mov_b32_e32 v98, 0
	v_mov_b32_e32 v114, 0
	v_mov_b32_e32 v99, 0
	v_mov_b32_e32 v115, 0
	v_mov_b32_e32 v100, 0
	v_mov_b32_e32 v116, 0
	v_mov_b32_e32 v101, 0
	v_mov_b32_e32 v117, 0
	v_mov_b32_e32 v102, 0
	v_mov_b32_e32 v118, 0
	v_mov_b32_e32 v103, 0
	v_mov_b32_e32 v119, 0
	v_mov_b32_e32 v104, 0
	v_mov_b32_e32 v120, 0
	v_mov_b32_e32 v105, 0
	v_mov_b32_e32 v121, 0
	v_mov_b32_e32 v106, 0
	v_mov_b32_e32 v122, 0
	v_mov_b32_e32 v107, 0
	v_mov_b32_e32 v123, 0
	v_mov_b32_e32 v108, 0
	v_mov_b32_e32 v124, 0
	v_mov_b32_e32 v109, 0
	v_mov_b32_e32 v125, 0
	v_mov_b32_e32 v110, 0
	v_mov_b32_e32 v126, 0
	v_mov_b32_e32 v111, 0
	v_mov_b32_e32 v127, 0
	s_mov_b64 s[24:25], s[20:21]
	global_load_dwordx4 v[32:35], v26, s[24:25]
	s_add_u32 s24, s24, 0x2000
	s_addc_u32 s25, s25, 0
	global_load_dwordx4 v[36:39], v26, s[24:25]
	s_add_u32 s24, s24, 0x2000
	s_addc_u32 s25, s25, 0
	global_load_dwordx4 v[40:43], v26, s[24:25]
	s_add_u32 s24, s24, 0x2000
	s_addc_u32 s25, s25, 0
	global_load_dwordx4 v[44:47], v26, s[24:25]
	s_add_u32 s24, s24, 0x2000
	s_addc_u32 s25, s25, 0
	global_load_dwordx4 v[48:51], v26, s[24:25]
	s_add_u32 s24, s24, 0x2000
	s_addc_u32 s25, s25, 0
	global_load_dwordx4 v[52:55], v26, s[24:25]
	s_add_u32 s24, s24, 0x2000
	s_addc_u32 s25, s25, 0
	global_load_dwordx4 v[56:59], v26, s[24:25]
	s_add_u32 s24, s24, 0x2000
	s_addc_u32 s25, s25, 0
	global_load_dwordx4 v[60:63], v26, s[24:25]
	s_add_u32 s24, s24, 0x2000
	s_addc_u32 s25, s25, 0
	global_load_dwordx4 v[64:67], v26, s[24:25]
	s_add_u32 s24, s24, 0x2000
	s_addc_u32 s25, s25, 0
	global_load_dwordx4 v[68:71], v26, s[24:25]
	s_add_u32 s24, s24, 0x2000
	s_addc_u32 s25, s25, 0
	global_load_dwordx4 v[72:75], v26, s[24:25]
	s_add_u32 s24, s24, 0x2000
	s_addc_u32 s25, s25, 0
	global_load_dwordx4 v[76:79], v26, s[24:25]
	s_add_u32 s24, s24, 0x2000
	s_addc_u32 s25, s25, 0
	global_load_dwordx4 v[80:83], v26, s[24:25]
	s_add_u32 s24, s24, 0x2000
	s_addc_u32 s25, s25, 0
	global_load_dwordx4 v[84:87], v26, s[24:25]
	s_add_u32 s24, s24, 0x2000
	s_addc_u32 s25, s25, 0
	global_load_dwordx4 v[88:91], v26, s[24:25]
	s_add_u32 s24, s24, 0x2000
	s_addc_u32 s25, s25, 0
	global_load_dwordx4 v[92:95], v26, s[24:25]
	v_cmp_ne_u32_e64 s[26:27], 0, v27
	s_and_saveexec_b64 s[0:1], s[26:27]
	s_mov_b64 s[24:25], s[20:21]
	global_load_ushort v96, v26, s[24:25] offset:-2
	s_add_u32 s24, s24, 0x2000
	s_addc_u32 s25, s25, 0
	global_load_ushort v97, v26, s[24:25] offset:-2
	s_add_u32 s24, s24, 0x2000
	s_addc_u32 s25, s25, 0
	global_load_ushort v98, v26, s[24:25] offset:-2
	s_add_u32 s24, s24, 0x2000
	s_addc_u32 s25, s25, 0
	global_load_ushort v99, v26, s[24:25] offset:-2
	s_add_u32 s24, s24, 0x2000
	s_addc_u32 s25, s25, 0
	global_load_ushort v100, v26, s[24:25] offset:-2
	s_add_u32 s24, s24, 0x2000
	s_addc_u32 s25, s25, 0
	global_load_ushort v101, v26, s[24:25] offset:-2
	s_add_u32 s24, s24, 0x2000
	s_addc_u32 s25, s25, 0
	global_load_ushort v102, v26, s[24:25] offset:-2
	s_add_u32 s24, s24, 0x2000
	s_addc_u32 s25, s25, 0
	global_load_ushort v103, v26, s[24:25] offset:-2
	s_add_u32 s24, s24, 0x2000
	s_addc_u32 s25, s25, 0
	global_load_ushort v104, v26, s[24:25] offset:-2
	s_add_u32 s24, s24, 0x2000
	s_addc_u32 s25, s25, 0
	global_load_ushort v105, v26, s[24:25] offset:-2
	s_add_u32 s24, s24, 0x2000
	s_addc_u32 s25, s25, 0
	global_load_ushort v106, v26, s[24:25] offset:-2
	s_add_u32 s24, s24, 0x2000
	s_addc_u32 s25, s25, 0
	global_load_ushort v107, v26, s[24:25] offset:-2
	s_add_u32 s24, s24, 0x2000
	s_addc_u32 s25, s25, 0
	global_load_ushort v108, v26, s[24:25] offset:-2
	s_add_u32 s24, s24, 0x2000
	s_addc_u32 s25, s25, 0
	global_load_ushort v109, v26, s[24:25] offset:-2
	s_add_u32 s24, s24, 0x2000
	s_addc_u32 s25, s25, 0
	global_load_ushort v110, v26, s[24:25] offset:-2
	s_add_u32 s24, s24, 0x2000
	s_addc_u32 s25, s25, 0
	global_load_ushort v111, v26, s[24:25] offset:-2
	s_mov_b64 exec, s[0:1]
	s_movk_i32 s24, 0x7f8
	v_cmp_ne_u32_e64 s[26:27], s24, v27
	s_and_saveexec_b64 s[0:1], s[26:27]
	s_mov_b64 s[24:25], s[20:21]
	global_load_ushort v112, v26, s[24:25] offset:16
	s_add_u32 s24, s24, 0x2000
	s_addc_u32 s25, s25, 0
	global_load_ushort v113, v26, s[24:25] offset:16
	s_add_u32 s24, s24, 0x2000
	s_addc_u32 s25, s25, 0
	global_load_ushort v114, v26, s[24:25] offset:16
	s_add_u32 s24, s24, 0x2000
	s_addc_u32 s25, s25, 0
	global_load_ushort v115, v26, s[24:25] offset:16
	s_add_u32 s24, s24, 0x2000
	s_addc_u32 s25, s25, 0
	global_load_ushort v116, v26, s[24:25] offset:16
	s_add_u32 s24, s24, 0x2000
	s_addc_u32 s25, s25, 0
	global_load_ushort v117, v26, s[24:25] offset:16
	s_add_u32 s24, s24, 0x2000
	s_addc_u32 s25, s25, 0
	global_load_ushort v118, v26, s[24:25] offset:16
	s_add_u32 s24, s24, 0x2000
	s_addc_u32 s25, s25, 0
	global_load_ushort v119, v26, s[24:25] offset:16
	s_add_u32 s24, s24, 0x2000
	s_addc_u32 s25, s25, 0
	global_load_ushort v120, v26, s[24:25] offset:16
	s_add_u32 s24, s24, 0x2000
	s_addc_u32 s25, s25, 0
	global_load_ushort v121, v26, s[24:25] offset:16
	s_add_u32 s24, s24, 0x2000
	s_addc_u32 s25, s25, 0
	global_load_ushort v122, v26, s[24:25] offset:16
	s_add_u32 s24, s24, 0x2000
	s_addc_u32 s25, s25, 0
	global_load_ushort v123, v26, s[24:25] offset:16
	s_add_u32 s24, s24, 0x2000
	s_addc_u32 s25, s25, 0
	global_load_ushort v124, v26, s[24:25] offset:16
	s_add_u32 s24, s24, 0x2000
	s_addc_u32 s25, s25, 0
	global_load_ushort v125, v26, s[24:25] offset:16
	s_add_u32 s24, s24, 0x2000
	s_addc_u32 s25, s25, 0
	global_load_ushort v126, v26, s[24:25] offset:16
	s_add_u32 s24, s24, 0x2000
	s_addc_u32 s25, s25, 0
	global_load_ushort v127, v26, s[24:25] offset:16
	s_mov_b64 exec, s[0:1]
	s_waitcnt vmcnt(0)
; __device__ __forceinline__ unsigned pk2(float lo, float hi) { unsigned r; asm("v_cvt_pk_bf16_f32 %0, %1, %2" : "=v"(r) : "v"(lo), "v"(hi)); return r; }
; __device__ __forceinline__ float bf2f(bf16_t b) { return __uint_as_float(((unsigned)b) << 16); }
; __device__ __forceinline__ float bflo(unsigned w) { return __uint_as_float(w << 16); }
; __device__ __forceinline__ float bfhi(unsigned w) { return __uint_as_float(w & 0xffff0000u); }
; __device__ __forceinline__ void hyena_unit(const Args& a, int L, int c, LAS unsigned char* lds) {
;     ...
;             float x[10];
;             x[0] = (s == 0) ? 0.f : bf2f(src[t0 - 1]);
;             x[1] = bflo(v.x); x[2] = bfhi(v.x); x[3] = bflo(v.y); x[4] = bfhi(v.y); x[5] = bflo(v.z); x[6] = bfhi(v.z); x[7] = bflo(v.w); x[8] = bfhi(v.w);
;             x[9] = (s == 2040) ? 0.f : bf2f(src[t0 + 8]);
;             float y[8];
; #pragma unroll
;             for (int j = 0; j < 8; ++j) y[j] = w0 * x[j] + w1 * x[j + 1] + w2 * x[j + 2] + bb;
;             u32x4 o; o.x = pk2(y[0], y[1]); o.y = pk2(y[2], y[3]); o.z = pk2(y[4], y[5]); o.w = pk2(y[6], y[7]);
;             *(u32x4*)(dst + t0) = o;
	s_mov_b64 s[24:25], s[22:23]
	v_lshlrev_b32_e32 v128, 16, v96
	v_lshlrev_b32_e32 v129, 16, v32
	v_and_b32_e32 v130, 0xffff0000, v32
	v_lshlrev_b32_e32 v131, 16, v33
	v_and_b32_e32 v132, 0xffff0000, v33
	v_lshlrev_b32_e32 v133, 16, v34
	v_and_b32_e32 v134, 0xffff0000, v34
	v_lshlrev_b32_e32 v135, 16, v35
	v_and_b32_e32 v136, 0xffff0000, v35
	v_lshlrev_b32_e32 v137, 16, v112
	v_mul_f32_e32 v8, v4, v128
	v_mul_f32_e32 v9, v4, v129
	v_mul_f32_e32 v10, v4, v130
	v_mul_f32_e32 v11, v4, v131
	v_mul_f32_e32 v12, v4, v132
	v_mul_f32_e32 v13, v4, v133
	v_mul_f32_e32 v14, v4, v134
	v_mul_f32_e32 v15, v4, v135
	v_fmac_f32_e32 v8, v7, v129
	v_fmac_f32_e32 v9, v7, v130
	v_fmac_f32_e32 v10, v7, v131
	v_fmac_f32_e32 v11, v7, v132
	v_fmac_f32_e32 v12, v7, v133
	v_fmac_f32_e32 v13, v7, v134
	v_fmac_f32_e32 v14, v7, v135
	v_fmac_f32_e32 v15, v7, v136
	v_fmac_f32_e32 v8, v6, v130
	v_fmac_f32_e32 v9, v6, v131
	v_fmac_f32_e32 v10, v6, v132
	v_fmac_f32_e32 v11, v6, v133
	v_fmac_f32_e32 v12, v6, v134
	v_fmac_f32_e32 v13, v6, v135
	v_fmac_f32_e32 v14, v6, v136
	v_fmac_f32_e32 v15, v6, v137
	v_add_f32_e32 v8, v18, v8
	v_add_f32_e32 v9, v18, v9
	v_add_f32_e32 v10, v18, v10
	v_add_f32_e32 v11, v18, v11
	v_add_f32_e32 v12, v18, v12
	v_add_f32_e32 v13, v18, v13
	v_add_f32_e32 v14, v18, v14
	v_add_f32_e32 v15, v18, v15
	v_cvt_pk_bf16_f32 v32, v8, v9
	v_cvt_pk_bf16_f32 v33, v10, v11
	v_cvt_pk_bf16_f32 v34, v12, v13
	v_cvt_pk_bf16_f32 v35, v14, v15
	global_store_dwordx4 v26, v[32:35], s[24:25]
	s_add_u32 s24, s24, 0x2000
	s_addc_u32 s25, s25, 0
	v_lshlrev_b32_e32 v128, 16, v97
	v_lshlrev_b32_e32 v129, 16, v36
	v_and_b32_e32 v130, 0xffff0000, v36
	v_lshlrev_b32_e32 v131, 16, v37
	v_and_b32_e32 v132, 0xffff0000, v37
	v_lshlrev_b32_e32 v133, 16, v38
	v_and_b32_e32 v134, 0xffff0000, v38
	v_lshlrev_b32_e32 v135, 16, v39
	v_and_b32_e32 v136, 0xffff0000, v39
	v_lshlrev_b32_e32 v137, 16, v113
	v_mul_f32_e32 v8, v4, v128
	v_mul_f32_e32 v9, v4, v129
	v_mul_f32_e32 v10, v4, v130
	v_mul_f32_e32 v11, v4, v131
	v_mul_f32_e32 v12, v4, v132
	v_mul_f32_e32 v13, v4, v133
	v_mul_f32_e32 v14, v4, v134
	v_mul_f32_e32 v15, v4, v135
	v_fmac_f32_e32 v8, v7, v129
	v_fmac_f32_e32 v9, v7, v130
	v_fmac_f32_e32 v10, v7, v131
	v_fmac_f32_e32 v11, v7, v132
	v_fmac_f32_e32 v12, v7, v133
	v_fmac_f32_e32 v13, v7, v134
	v_fmac_f32_e32 v14, v7, v135
	v_fmac_f32_e32 v15, v7, v136
	v_fmac_f32_e32 v8, v6, v130
	v_fmac_f32_e32 v9, v6, v131
	v_fmac_f32_e32 v10, v6, v132
	v_fmac_f32_e32 v11, v6, v133
	v_fmac_f32_e32 v12, v6, v134
	v_fmac_f32_e32 v13, v6, v135
	v_fmac_f32_e32 v14, v6, v136
	v_fmac_f32_e32 v15, v6, v137
	v_add_f32_e32 v8, v18, v8
	v_add_f32_e32 v9, v18, v9
	v_add_f32_e32 v10, v18, v10
	v_add_f32_e32 v11, v18, v11
	v_add_f32_e32 v12, v18, v12
	v_add_f32_e32 v13, v18, v13
	v_add_f32_e32 v14, v18, v14
	v_add_f32_e32 v15, v18, v15
	v_cvt_pk_bf16_f32 v36, v8, v9
	v_cvt_pk_bf16_f32 v37, v10, v11
	v_cvt_pk_bf16_f32 v38, v12, v13
	v_cvt_pk_bf16_f32 v39, v14, v15
	global_store_dwordx4 v26, v[36:39], s[24:25]
	s_add_u32 s24, s24, 0x2000
	s_addc_u32 s25, s25, 0
	v_lshlrev_b32_e32 v128, 16, v98
	v_lshlrev_b32_e32 v129, 16, v40
	v_and_b32_e32 v130, 0xffff0000, v40
	v_lshlrev_b32_e32 v131, 16, v41
	v_and_b32_e32 v132, 0xffff0000, v41
	v_lshlrev_b32_e32 v133, 16, v42
	v_and_b32_e32 v134, 0xffff0000, v42
	v_lshlrev_b32_e32 v135, 16, v43
	v_and_b32_e32 v136, 0xffff0000, v43
	v_lshlrev_b32_e32 v137, 16, v114
	v_mul_f32_e32 v8, v4, v128
	v_mul_f32_e32 v9, v4, v129
	v_mul_f32_e32 v10, v4, v130
	v_mul_f32_e32 v11, v4, v131
	v_mul_f32_e32 v12, v4, v132
	v_mul_f32_e32 v13, v4, v133
	v_mul_f32_e32 v14, v4, v134
	v_mul_f32_e32 v15, v4, v135
	v_fmac_f32_e32 v8, v7, v129
	v_fmac_f32_e32 v9, v7, v130
	v_fmac_f32_e32 v10, v7, v131
	v_fmac_f32_e32 v11, v7, v132
	v_fmac_f32_e32 v12, v7, v133
	v_fmac_f32_e32 v13, v7, v134
	v_fmac_f32_e32 v14, v7, v135
	v_fmac_f32_e32 v15, v7, v136
	v_fmac_f32_e32 v8, v6, v130
	v_fmac_f32_e32 v9, v6, v131
	v_fmac_f32_e32 v10, v6, v132
	v_fmac_f32_e32 v11, v6, v133
	v_fmac_f32_e32 v12, v6, v134
	v_fmac_f32_e32 v13, v6, v135
	v_fmac_f32_e32 v14, v6, v136
	v_fmac_f32_e32 v15, v6, v137
	v_add_f32_e32 v8, v18, v8
	v_add_f32_e32 v9, v18, v9
	v_add_f32_e32 v10, v18, v10
	v_add_f32_e32 v11, v18, v11
	v_add_f32_e32 v12, v18, v12
	v_add_f32_e32 v13, v18, v13
	v_add_f32_e32 v14, v18, v14
	v_add_f32_e32 v15, v18, v15
	v_cvt_pk_bf16_f32 v40, v8, v9
	v_cvt_pk_bf16_f32 v41, v10, v11
	v_cvt_pk_bf16_f32 v42, v12, v13
	v_cvt_pk_bf16_f32 v43, v14, v15
	global_store_dwordx4 v26, v[40:43], s[24:25]
	s_add_u32 s24, s24, 0x2000
	s_addc_u32 s25, s25, 0
	v_lshlrev_b32_e32 v128, 16, v99
	v_lshlrev_b32_e32 v129, 16, v44
	v_and_b32_e32 v130, 0xffff0000, v44
	v_lshlrev_b32_e32 v131, 16, v45
	v_and_b32_e32 v132, 0xffff0000, v45
	v_lshlrev_b32_e32 v133, 16, v46
	v_and_b32_e32 v134, 0xffff0000, v46
	v_lshlrev_b32_e32 v135, 16, v47
	v_and_b32_e32 v136, 0xffff0000, v47
	v_lshlrev_b32_e32 v137, 16, v115
	v_mul_f32_e32 v8, v4, v128
	v_mul_f32_e32 v9, v4, v129
	v_mul_f32_e32 v10, v4, v130
	v_mul_f32_e32 v11, v4, v131
	v_mul_f32_e32 v12, v4, v132
	v_mul_f32_e32 v13, v4, v133
	v_mul_f32_e32 v14, v4, v134
	v_mul_f32_e32 v15, v4, v135
	v_fmac_f32_e32 v8, v7, v129
	v_fmac_f32_e32 v9, v7, v130
	v_fmac_f32_e32 v10, v7, v131
	v_fmac_f32_e32 v11, v7, v132
	v_fmac_f32_e32 v12, v7, v133
	v_fmac_f32_e32 v13, v7, v134
	v_fmac_f32_e32 v14, v7, v135
	v_fmac_f32_e32 v15, v7, v136
	v_fmac_f32_e32 v8, v6, v130
	v_fmac_f32_e32 v9, v6, v131
	v_fmac_f32_e32 v10, v6, v132
	v_fmac_f32_e32 v11, v6, v133
	v_fmac_f32_e32 v12, v6, v134
	v_fmac_f32_e32 v13, v6, v135
	v_fmac_f32_e32 v14, v6, v136
	v_fmac_f32_e32 v15, v6, v137
	v_add_f32_e32 v8, v18, v8
; __device__ __forceinline__ unsigned pk2(float lo, float hi) { unsigned r; asm("v_cvt_pk_bf16_f32 %0, %1, %2" : "=v"(r) : "v"(lo), "v"(hi)); return r; }
; __device__ __forceinline__ float bf2f(bf16_t b) { return __uint_as_float(((unsigned)b) << 16); }
; __device__ __forceinline__ float bflo(unsigned w) { return __uint_as_float(w << 16); }
; __device__ __forceinline__ float bfhi(unsigned w) { return __uint_as_float(w & 0xffff0000u); }
; __device__ __forceinline__ void hyena_unit(const Args& a, int L, int c, LAS unsigned char* lds) {
;     ...
;             float x[10];
;             x[0] = (s == 0) ? 0.f : bf2f(src[t0 - 1]);
;             x[1] = bflo(v.x); x[2] = bfhi(v.x); x[3] = bflo(v.y); x[4] = bfhi(v.y); x[5] = bflo(v.z); x[6] = bfhi(v.z); x[7] = bflo(v.w); x[8] = bfhi(v.w);
;             x[9] = (s == 2040) ? 0.f : bf2f(src[t0 + 8]);
;             float y[8];
; #pragma unroll
;             for (int j = 0; j < 8; ++j) y[j] = w0 * x[j] + w1 * x[j + 1] + w2 * x[j + 2] + bb;
;             u32x4 o; o.x = pk2(y[0], y[1]); o.y = pk2(y[2], y[3]); o.z = pk2(y[4], y[5]); o.w = pk2(y[6], y[7]);
;             *(u32x4*)(dst + t0) = o;
	v_add_f32_e32 v9, v18, v9
	v_add_f32_e32 v10, v18, v10
	v_add_f32_e32 v11, v18, v11
	v_add_f32_e32 v12, v18, v12
	v_add_f32_e32 v13, v18, v13
	v_add_f32_e32 v14, v18, v14
	v_add_f32_e32 v15, v18, v15
	v_cvt_pk_bf16_f32 v44, v8, v9
	v_cvt_pk_bf16_f32 v45, v10, v11
	v_cvt_pk_bf16_f32 v46, v12, v13
	v_cvt_pk_bf16_f32 v47, v14, v15
	global_store_dwordx4 v26, v[44:47], s[24:25]
	s_add_u32 s24, s24, 0x2000
	s_addc_u32 s25, s25, 0
	v_lshlrev_b32_e32 v128, 16, v100
	v_lshlrev_b32_e32 v129, 16, v48
	v_and_b32_e32 v130, 0xffff0000, v48
	v_lshlrev_b32_e32 v131, 16, v49
	v_and_b32_e32 v132, 0xffff0000, v49
	v_lshlrev_b32_e32 v133, 16, v50
	v_and_b32_e32 v134, 0xffff0000, v50
	v_lshlrev_b32_e32 v135, 16, v51
	v_and_b32_e32 v136, 0xffff0000, v51
	v_lshlrev_b32_e32 v137, 16, v116
	v_mul_f32_e32 v8, v4, v128
	v_mul_f32_e32 v9, v4, v129
	v_mul_f32_e32 v10, v4, v130
	v_mul_f32_e32 v11, v4, v131
	v_mul_f32_e32 v12, v4, v132
	v_mul_f32_e32 v13, v4, v133
	v_mul_f32_e32 v14, v4, v134
	v_mul_f32_e32 v15, v4, v135
	v_fmac_f32_e32 v8, v7, v129
	v_fmac_f32_e32 v9, v7, v130
	v_fmac_f32_e32 v10, v7, v131
	v_fmac_f32_e32 v11, v7, v132
	v_fmac_f32_e32 v12, v7, v133
	v_fmac_f32_e32 v13, v7, v134
	v_fmac_f32_e32 v14, v7, v135
	v_fmac_f32_e32 v15, v7, v136
	v_fmac_f32_e32 v8, v6, v130
	v_fmac_f32_e32 v9, v6, v131
	v_fmac_f32_e32 v10, v6, v132
	v_fmac_f32_e32 v11, v6, v133
	v_fmac_f32_e32 v12, v6, v134
	v_fmac_f32_e32 v13, v6, v135
	v_fmac_f32_e32 v14, v6, v136
	v_fmac_f32_e32 v15, v6, v137
	v_add_f32_e32 v8, v18, v8
	v_add_f32_e32 v9, v18, v9
	v_add_f32_e32 v10, v18, v10
	v_add_f32_e32 v11, v18, v11
	v_add_f32_e32 v12, v18, v12
	v_add_f32_e32 v13, v18, v13
	v_add_f32_e32 v14, v18, v14
	v_add_f32_e32 v15, v18, v15
	v_cvt_pk_bf16_f32 v48, v8, v9
	v_cvt_pk_bf16_f32 v49, v10, v11
	v_cvt_pk_bf16_f32 v50, v12, v13
	v_cvt_pk_bf16_f32 v51, v14, v15
	global_store_dwordx4 v26, v[48:51], s[24:25]
	s_add_u32 s24, s24, 0x2000
	s_addc_u32 s25, s25, 0
	v_lshlrev_b32_e32 v128, 16, v101
	v_lshlrev_b32_e32 v129, 16, v52
	v_and_b32_e32 v130, 0xffff0000, v52
	v_lshlrev_b32_e32 v131, 16, v53
	v_and_b32_e32 v132, 0xffff0000, v53
	v_lshlrev_b32_e32 v133, 16, v54
	v_and_b32_e32 v134, 0xffff0000, v54
	v_lshlrev_b32_e32 v135, 16, v55
	v_and_b32_e32 v136, 0xffff0000, v55
	v_lshlrev_b32_e32 v137, 16, v117
	v_mul_f32_e32 v8, v4, v128
	v_mul_f32_e32 v9, v4, v129
	v_mul_f32_e32 v10, v4, v130
	v_mul_f32_e32 v11, v4, v131
	v_mul_f32_e32 v12, v4, v132
	v_mul_f32_e32 v13, v4, v133
	v_mul_f32_e32 v14, v4, v134
	v_mul_f32_e32 v15, v4, v135
	v_fmac_f32_e32 v8, v7, v129
	v_fmac_f32_e32 v9, v7, v130
	v_fmac_f32_e32 v10, v7, v131
	v_fmac_f32_e32 v11, v7, v132
	v_fmac_f32_e32 v12, v7, v133
	v_fmac_f32_e32 v13, v7, v134
	v_fmac_f32_e32 v14, v7, v135
	v_fmac_f32_e32 v15, v7, v136
	v_fmac_f32_e32 v8, v6, v130
	v_fmac_f32_e32 v9, v6, v131
	v_fmac_f32_e32 v10, v6, v132
	v_fmac_f32_e32 v11, v6, v133
	v_fmac_f32_e32 v12, v6, v134
	v_fmac_f32_e32 v13, v6, v135
	v_fmac_f32_e32 v14, v6, v136
	v_fmac_f32_e32 v15, v6, v137
	v_add_f32_e32 v8, v18, v8
	v_add_f32_e32 v9, v18, v9
	v_add_f32_e32 v10, v18, v10
	v_add_f32_e32 v11, v18, v11
	v_add_f32_e32 v12, v18, v12
	v_add_f32_e32 v13, v18, v13
	v_add_f32_e32 v14, v18, v14
	v_add_f32_e32 v15, v18, v15
	v_cvt_pk_bf16_f32 v52, v8, v9
	v_cvt_pk_bf16_f32 v53, v10, v11
	v_cvt_pk_bf16_f32 v54, v12, v13
	v_cvt_pk_bf16_f32 v55, v14, v15
	global_store_dwordx4 v26, v[52:55], s[24:25]
	s_add_u32 s24, s24, 0x2000
	s_addc_u32 s25, s25, 0
	v_lshlrev_b32_e32 v128, 16, v102
	v_lshlrev_b32_e32 v129, 16, v56
	v_and_b32_e32 v130, 0xffff0000, v56
	v_lshlrev_b32_e32 v131, 16, v57
	v_and_b32_e32 v132, 0xffff0000, v57
	v_lshlrev_b32_e32 v133, 16, v58
	v_and_b32_e32 v134, 0xffff0000, v58
	v_lshlrev_b32_e32 v135, 16, v59
	v_and_b32_e32 v136, 0xffff0000, v59
	v_lshlrev_b32_e32 v137, 16, v118
	v_mul_f32_e32 v8, v4, v128
	v_mul_f32_e32 v9, v4, v129
	v_mul_f32_e32 v10, v4, v130
	v_mul_f32_e32 v11, v4, v131
	v_mul_f32_e32 v12, v4, v132
	v_mul_f32_e32 v13, v4, v133
	v_mul_f32_e32 v14, v4, v134
	v_mul_f32_e32 v15, v4, v135
	v_fmac_f32_e32 v8, v7, v129
	v_fmac_f32_e32 v9, v7, v130
	v_fmac_f32_e32 v10, v7, v131
	v_fmac_f32_e32 v11, v7, v132
	v_fmac_f32_e32 v12, v7, v133
	v_fmac_f32_e32 v13, v7, v134
	v_fmac_f32_e32 v14, v7, v135
	v_fmac_f32_e32 v15, v7, v136
	v_fmac_f32_e32 v8, v6, v130
	v_fmac_f32_e32 v9, v6, v131
	v_fmac_f32_e32 v10, v6, v132
	v_fmac_f32_e32 v11, v6, v133
	v_fmac_f32_e32 v12, v6, v134
	v_fmac_f32_e32 v13, v6, v135
	v_fmac_f32_e32 v14, v6, v136
	v_fmac_f32_e32 v15, v6, v137
	v_add_f32_e32 v8, v18, v8
	v_add_f32_e32 v9, v18, v9
	v_add_f32_e32 v10, v18, v10
	v_add_f32_e32 v11, v18, v11
	v_add_f32_e32 v12, v18, v12
	v_add_f32_e32 v13, v18, v13
	v_add_f32_e32 v14, v18, v14
	v_add_f32_e32 v15, v18, v15
	v_cvt_pk_bf16_f32 v56, v8, v9
	v_cvt_pk_bf16_f32 v57, v10, v11
	v_cvt_pk_bf16_f32 v58, v12, v13
	v_cvt_pk_bf16_f32 v59, v14, v15
	global_store_dwordx4 v26, v[56:59], s[24:25]
	s_add_u32 s24, s24, 0x2000
	s_addc_u32 s25, s25, 0
	v_lshlrev_b32_e32 v128, 16, v103
	v_lshlrev_b32_e32 v129, 16, v60
	v_and_b32_e32 v130, 0xffff0000, v60
	v_lshlrev_b32_e32 v131, 16, v61
	v_and_b32_e32 v132, 0xffff0000, v61
	v_lshlrev_b32_e32 v133, 16, v62
	v_and_b32_e32 v134, 0xffff0000, v62
	v_lshlrev_b32_e32 v135, 16, v63
	v_and_b32_e32 v136, 0xffff0000, v63
	v_lshlrev_b32_e32 v137, 16, v119
	v_mul_f32_e32 v8, v4, v128
	v_mul_f32_e32 v9, v4, v129
	v_mul_f32_e32 v10, v4, v130
	v_mul_f32_e32 v11, v4, v131
	v_mul_f32_e32 v12, v4, v132
	v_mul_f32_e32 v13, v4, v133
	v_mul_f32_e32 v14, v4, v134
	v_mul_f32_e32 v15, v4, v135
	v_fmac_f32_e32 v8, v7, v129
	v_fmac_f32_e32 v9, v7, v130
	v_fmac_f32_e32 v10, v7, v131
; __device__ __forceinline__ unsigned pk2(float lo, float hi) { unsigned r; asm("v_cvt_pk_bf16_f32 %0, %1, %2" : "=v"(r) : "v"(lo), "v"(hi)); return r; }
; __device__ __forceinline__ float bf2f(bf16_t b) { return __uint_as_float(((unsigned)b) << 16); }
; __device__ __forceinline__ float bflo(unsigned w) { return __uint_as_float(w << 16); }
; __device__ __forceinline__ float bfhi(unsigned w) { return __uint_as_float(w & 0xffff0000u); }
; __device__ __forceinline__ void hyena_unit(const Args& a, int L, int c, LAS unsigned char* lds) {
;     ...
;             float x[10];
;             x[0] = (s == 0) ? 0.f : bf2f(src[t0 - 1]);
;             x[1] = bflo(v.x); x[2] = bfhi(v.x); x[3] = bflo(v.y); x[4] = bfhi(v.y); x[5] = bflo(v.z); x[6] = bfhi(v.z); x[7] = bflo(v.w); x[8] = bfhi(v.w);
;             x[9] = (s == 2040) ? 0.f : bf2f(src[t0 + 8]);
;             float y[8];
; #pragma unroll
;             for (int j = 0; j < 8; ++j) y[j] = w0 * x[j] + w1 * x[j + 1] + w2 * x[j + 2] + bb;
;             u32x4 o; o.x = pk2(y[0], y[1]); o.y = pk2(y[2], y[3]); o.z = pk2(y[4], y[5]); o.w = pk2(y[6], y[7]);
;             *(u32x4*)(dst + t0) = o;
	v_fmac_f32_e32 v11, v7, v132
	v_fmac_f32_e32 v12, v7, v133
	v_fmac_f32_e32 v13, v7, v134
	v_fmac_f32_e32 v14, v7, v135
	v_fmac_f32_e32 v15, v7, v136
	v_fmac_f32_e32 v8, v6, v130
	v_fmac_f32_e32 v9, v6, v131
	v_fmac_f32_e32 v10, v6, v132
	v_fmac_f32_e32 v11, v6, v133
	v_fmac_f32_e32 v12, v6, v134
	v_fmac_f32_e32 v13, v6, v135
	v_fmac_f32_e32 v14, v6, v136
	v_fmac_f32_e32 v15, v6, v137
	v_add_f32_e32 v8, v18, v8
	v_add_f32_e32 v9, v18, v9
	v_add_f32_e32 v10, v18, v10
	v_add_f32_e32 v11, v18, v11
	v_add_f32_e32 v12, v18, v12
	v_add_f32_e32 v13, v18, v13
	v_add_f32_e32 v14, v18, v14
	v_add_f32_e32 v15, v18, v15
	v_cvt_pk_bf16_f32 v60, v8, v9
	v_cvt_pk_bf16_f32 v61, v10, v11
	v_cvt_pk_bf16_f32 v62, v12, v13
	v_cvt_pk_bf16_f32 v63, v14, v15
	global_store_dwordx4 v26, v[60:63], s[24:25]
	s_add_u32 s24, s24, 0x2000
	s_addc_u32 s25, s25, 0
	v_lshlrev_b32_e32 v128, 16, v104
	v_lshlrev_b32_e32 v129, 16, v64
	v_and_b32_e32 v130, 0xffff0000, v64
	v_lshlrev_b32_e32 v131, 16, v65
	v_and_b32_e32 v132, 0xffff0000, v65
	v_lshlrev_b32_e32 v133, 16, v66
	v_and_b32_e32 v134, 0xffff0000, v66
	v_lshlrev_b32_e32 v135, 16, v67
	v_and_b32_e32 v136, 0xffff0000, v67
	v_lshlrev_b32_e32 v137, 16, v120
	v_mul_f32_e32 v8, v4, v128
	v_mul_f32_e32 v9, v4, v129
	v_mul_f32_e32 v10, v4, v130
	v_mul_f32_e32 v11, v4, v131
	v_mul_f32_e32 v12, v4, v132
	v_mul_f32_e32 v13, v4, v133
	v_mul_f32_e32 v14, v4, v134
	v_mul_f32_e32 v15, v4, v135
	v_fmac_f32_e32 v8, v7, v129
	v_fmac_f32_e32 v9, v7, v130
	v_fmac_f32_e32 v10, v7, v131
	v_fmac_f32_e32 v11, v7, v132
	v_fmac_f32_e32 v12, v7, v133
	v_fmac_f32_e32 v13, v7, v134
	v_fmac_f32_e32 v14, v7, v135
	v_fmac_f32_e32 v15, v7, v136
	v_fmac_f32_e32 v8, v6, v130
	v_fmac_f32_e32 v9, v6, v131
	v_fmac_f32_e32 v10, v6, v132
	v_fmac_f32_e32 v11, v6, v133
	v_fmac_f32_e32 v12, v6, v134
	v_fmac_f32_e32 v13, v6, v135
	v_fmac_f32_e32 v14, v6, v136
	v_fmac_f32_e32 v15, v6, v137
	v_add_f32_e32 v8, v18, v8
	v_add_f32_e32 v9, v18, v9
	v_add_f32_e32 v10, v18, v10
	v_add_f32_e32 v11, v18, v11
	v_add_f32_e32 v12, v18, v12
	v_add_f32_e32 v13, v18, v13
	v_add_f32_e32 v14, v18, v14
	v_add_f32_e32 v15, v18, v15
	v_cvt_pk_bf16_f32 v64, v8, v9
	v_cvt_pk_bf16_f32 v65, v10, v11
	v_cvt_pk_bf16_f32 v66, v12, v13
	v_cvt_pk_bf16_f32 v67, v14, v15
	global_store_dwordx4 v26, v[64:67], s[24:25]
	s_add_u32 s24, s24, 0x2000
	s_addc_u32 s25, s25, 0
	v_lshlrev_b32_e32 v128, 16, v105
	v_lshlrev_b32_e32 v129, 16, v68
	v_and_b32_e32 v130, 0xffff0000, v68
	v_lshlrev_b32_e32 v131, 16, v69
	v_and_b32_e32 v132, 0xffff0000, v69
	v_lshlrev_b32_e32 v133, 16, v70
	v_and_b32_e32 v134, 0xffff0000, v70
	v_lshlrev_b32_e32 v135, 16, v71
	v_and_b32_e32 v136, 0xffff0000, v71
	v_lshlrev_b32_e32 v137, 16, v121
	v_mul_f32_e32 v8, v4, v128
	v_mul_f32_e32 v9, v4, v129
	v_mul_f32_e32 v10, v4, v130
	v_mul_f32_e32 v11, v4, v131
	v_mul_f32_e32 v12, v4, v132
	v_mul_f32_e32 v13, v4, v133
	v_mul_f32_e32 v14, v4, v134
	v_mul_f32_e32 v15, v4, v135
	v_fmac_f32_e32 v8, v7, v129
	v_fmac_f32_e32 v9, v7, v130
	v_fmac_f32_e32 v10, v7, v131
	v_fmac_f32_e32 v11, v7, v132
	v_fmac_f32_e32 v12, v7, v133
	v_fmac_f32_e32 v13, v7, v134
	v_fmac_f32_e32 v14, v7, v135
	v_fmac_f32_e32 v15, v7, v136
	v_fmac_f32_e32 v8, v6, v130
	v_fmac_f32_e32 v9, v6, v131
	v_fmac_f32_e32 v10, v6, v132
	v_fmac_f32_e32 v11, v6, v133
	v_fmac_f32_e32 v12, v6, v134
	v_fmac_f32_e32 v13, v6, v135
	v_fmac_f32_e32 v14, v6, v136
	v_fmac_f32_e32 v15, v6, v137
	v_add_f32_e32 v8, v18, v8
	v_add_f32_e32 v9, v18, v9
	v_add_f32_e32 v10, v18, v10
	v_add_f32_e32 v11, v18, v11
	v_add_f32_e32 v12, v18, v12
	v_add_f32_e32 v13, v18, v13
	v_add_f32_e32 v14, v18, v14
	v_add_f32_e32 v15, v18, v15
	v_cvt_pk_bf16_f32 v68, v8, v9
	v_cvt_pk_bf16_f32 v69, v10, v11
	v_cvt_pk_bf16_f32 v70, v12, v13
	v_cvt_pk_bf16_f32 v71, v14, v15
	global_store_dwordx4 v26, v[68:71], s[24:25]
	s_add_u32 s24, s24, 0x2000
	s_addc_u32 s25, s25, 0
	v_lshlrev_b32_e32 v128, 16, v106
	v_lshlrev_b32_e32 v129, 16, v72
	v_and_b32_e32 v130, 0xffff0000, v72
	v_lshlrev_b32_e32 v131, 16, v73
	v_and_b32_e32 v132, 0xffff0000, v73
	v_lshlrev_b32_e32 v133, 16, v74
	v_and_b32_e32 v134, 0xffff0000, v74
	v_lshlrev_b32_e32 v135, 16, v75
	v_and_b32_e32 v136, 0xffff0000, v75
	v_lshlrev_b32_e32 v137, 16, v122
	v_mul_f32_e32 v8, v4, v128
	v_mul_f32_e32 v9, v4, v129
	v_mul_f32_e32 v10, v4, v130
	v_mul_f32_e32 v11, v4, v131
	v_mul_f32_e32 v12, v4, v132
	v_mul_f32_e32 v13, v4, v133
	v_mul_f32_e32 v14, v4, v134
	v_mul_f32_e32 v15, v4, v135
	v_fmac_f32_e32 v8, v7, v129
	v_fmac_f32_e32 v9, v7, v130
	v_fmac_f32_e32 v10, v7, v131
	v_fmac_f32_e32 v11, v7, v132
	v_fmac_f32_e32 v12, v7, v133
	v_fmac_f32_e32 v13, v7, v134
	v_fmac_f32_e32 v14, v7, v135
	v_fmac_f32_e32 v15, v7, v136
	v_fmac_f32_e32 v8, v6, v130
	v_fmac_f32_e32 v9, v6, v131
	v_fmac_f32_e32 v10, v6, v132
	v_fmac_f32_e32 v11, v6, v133
	v_fmac_f32_e32 v12, v6, v134
	v_fmac_f32_e32 v13, v6, v135
	v_fmac_f32_e32 v14, v6, v136
	v_fmac_f32_e32 v15, v6, v137
	v_add_f32_e32 v8, v18, v8
	v_add_f32_e32 v9, v18, v9
	v_add_f32_e32 v10, v18, v10
	v_add_f32_e32 v11, v18, v11
	v_add_f32_e32 v12, v18, v12
	v_add_f32_e32 v13, v18, v13
	v_add_f32_e32 v14, v18, v14
	v_add_f32_e32 v15, v18, v15
	v_cvt_pk_bf16_f32 v72, v8, v9
	v_cvt_pk_bf16_f32 v73, v10, v11
	v_cvt_pk_bf16_f32 v74, v12, v13
	v_cvt_pk_bf16_f32 v75, v14, v15
	global_store_dwordx4 v26, v[72:75], s[24:25]
	s_add_u32 s24, s24, 0x2000
	s_addc_u32 s25, s25, 0
	v_lshlrev_b32_e32 v128, 16, v107
	v_lshlrev_b32_e32 v129, 16, v76
	v_and_b32_e32 v130, 0xffff0000, v76
	v_lshlrev_b32_e32 v131, 16, v77
	v_and_b32_e32 v132, 0xffff0000, v77
	v_lshlrev_b32_e32 v133, 16, v78
	v_and_b32_e32 v134, 0xffff0000, v78
	v_lshlrev_b32_e32 v135, 16, v79
; __device__ __forceinline__ unsigned pk2(float lo, float hi) { unsigned r; asm("v_cvt_pk_bf16_f32 %0, %1, %2" : "=v"(r) : "v"(lo), "v"(hi)); return r; }
; __device__ __forceinline__ float bf2f(bf16_t b) { return __uint_as_float(((unsigned)b) << 16); }
; __device__ __forceinline__ float bflo(unsigned w) { return __uint_as_float(w << 16); }
; __device__ __forceinline__ float bfhi(unsigned w) { return __uint_as_float(w & 0xffff0000u); }
; __device__ __forceinline__ void hyena_unit(const Args& a, int L, int c, LAS unsigned char* lds) {
;     ...
;             float x[10];
;             x[0] = (s == 0) ? 0.f : bf2f(src[t0 - 1]);
;             x[1] = bflo(v.x); x[2] = bfhi(v.x); x[3] = bflo(v.y); x[4] = bfhi(v.y); x[5] = bflo(v.z); x[6] = bfhi(v.z); x[7] = bflo(v.w); x[8] = bfhi(v.w);
;             x[9] = (s == 2040) ? 0.f : bf2f(src[t0 + 8]);
;             float y[8];
; #pragma unroll
;             for (int j = 0; j < 8; ++j) y[j] = w0 * x[j] + w1 * x[j + 1] + w2 * x[j + 2] + bb;
;             u32x4 o; o.x = pk2(y[0], y[1]); o.y = pk2(y[2], y[3]); o.z = pk2(y[4], y[5]); o.w = pk2(y[6], y[7]);
;             *(u32x4*)(dst + t0) = o;
	v_and_b32_e32 v136, 0xffff0000, v79
	v_lshlrev_b32_e32 v137, 16, v123
	v_mul_f32_e32 v8, v4, v128
	v_mul_f32_e32 v9, v4, v129
	v_mul_f32_e32 v10, v4, v130
	v_mul_f32_e32 v11, v4, v131
	v_mul_f32_e32 v12, v4, v132
	v_mul_f32_e32 v13, v4, v133
	v_mul_f32_e32 v14, v4, v134
	v_mul_f32_e32 v15, v4, v135
	v_fmac_f32_e32 v8, v7, v129
	v_fmac_f32_e32 v9, v7, v130
	v_fmac_f32_e32 v10, v7, v131
	v_fmac_f32_e32 v11, v7, v132
	v_fmac_f32_e32 v12, v7, v133
	v_fmac_f32_e32 v13, v7, v134
	v_fmac_f32_e32 v14, v7, v135
	v_fmac_f32_e32 v15, v7, v136
	v_fmac_f32_e32 v8, v6, v130
	v_fmac_f32_e32 v9, v6, v131
	v_fmac_f32_e32 v10, v6, v132
	v_fmac_f32_e32 v11, v6, v133
	v_fmac_f32_e32 v12, v6, v134
	v_fmac_f32_e32 v13, v6, v135
	v_fmac_f32_e32 v14, v6, v136
	v_fmac_f32_e32 v15, v6, v137
	v_add_f32_e32 v8, v18, v8
	v_add_f32_e32 v9, v18, v9
	v_add_f32_e32 v10, v18, v10
	v_add_f32_e32 v11, v18, v11
	v_add_f32_e32 v12, v18, v12
	v_add_f32_e32 v13, v18, v13
	v_add_f32_e32 v14, v18, v14
	v_add_f32_e32 v15, v18, v15
	v_cvt_pk_bf16_f32 v76, v8, v9
	v_cvt_pk_bf16_f32 v77, v10, v11
	v_cvt_pk_bf16_f32 v78, v12, v13
	v_cvt_pk_bf16_f32 v79, v14, v15
	global_store_dwordx4 v26, v[76:79], s[24:25]
	s_add_u32 s24, s24, 0x2000
	s_addc_u32 s25, s25, 0
	v_lshlrev_b32_e32 v128, 16, v108
	v_lshlrev_b32_e32 v129, 16, v80
	v_and_b32_e32 v130, 0xffff0000, v80
	v_lshlrev_b32_e32 v131, 16, v81
	v_and_b32_e32 v132, 0xffff0000, v81
	v_lshlrev_b32_e32 v133, 16, v82
	v_and_b32_e32 v134, 0xffff0000, v82
	v_lshlrev_b32_e32 v135, 16, v83
	v_and_b32_e32 v136, 0xffff0000, v83
	v_lshlrev_b32_e32 v137, 16, v124
	v_mul_f32_e32 v8, v4, v128
	v_mul_f32_e32 v9, v4, v129
	v_mul_f32_e32 v10, v4, v130
	v_mul_f32_e32 v11, v4, v131
	v_mul_f32_e32 v12, v4, v132
	v_mul_f32_e32 v13, v4, v133
	v_mul_f32_e32 v14, v4, v134
	v_mul_f32_e32 v15, v4, v135
	v_fmac_f32_e32 v8, v7, v129
	v_fmac_f32_e32 v9, v7, v130
	v_fmac_f32_e32 v10, v7, v131
	v_fmac_f32_e32 v11, v7, v132
	v_fmac_f32_e32 v12, v7, v133
	v_fmac_f32_e32 v13, v7, v134
	v_fmac_f32_e32 v14, v7, v135
	v_fmac_f32_e32 v15, v7, v136
	v_fmac_f32_e32 v8, v6, v130
	v_fmac_f32_e32 v9, v6, v131
	v_fmac_f32_e32 v10, v6, v132
	v_fmac_f32_e32 v11, v6, v133
	v_fmac_f32_e32 v12, v6, v134
	v_fmac_f32_e32 v13, v6, v135
	v_fmac_f32_e32 v14, v6, v136
	v_fmac_f32_e32 v15, v6, v137
	v_add_f32_e32 v8, v18, v8
	v_add_f32_e32 v9, v18, v9
	v_add_f32_e32 v10, v18, v10
	v_add_f32_e32 v11, v18, v11
	v_add_f32_e32 v12, v18, v12
	v_add_f32_e32 v13, v18, v13
	v_add_f32_e32 v14, v18, v14
	v_add_f32_e32 v15, v18, v15
	v_cvt_pk_bf16_f32 v80, v8, v9
	v_cvt_pk_bf16_f32 v81, v10, v11
	v_cvt_pk_bf16_f32 v82, v12, v13
	v_cvt_pk_bf16_f32 v83, v14, v15
	global_store_dwordx4 v26, v[80:83], s[24:25]
	s_add_u32 s24, s24, 0x2000
	s_addc_u32 s25, s25, 0
	v_lshlrev_b32_e32 v128, 16, v109
	v_lshlrev_b32_e32 v129, 16, v84
	v_and_b32_e32 v130, 0xffff0000, v84
	v_lshlrev_b32_e32 v131, 16, v85
	v_and_b32_e32 v132, 0xffff0000, v85
	v_lshlrev_b32_e32 v133, 16, v86
	v_and_b32_e32 v134, 0xffff0000, v86
	v_lshlrev_b32_e32 v135, 16, v87
	v_and_b32_e32 v136, 0xffff0000, v87
	v_lshlrev_b32_e32 v137, 16, v125
	v_mul_f32_e32 v8, v4, v128
	v_mul_f32_e32 v9, v4, v129
	v_mul_f32_e32 v10, v4, v130
	v_mul_f32_e32 v11, v4, v131
	v_mul_f32_e32 v12, v4, v132
	v_mul_f32_e32 v13, v4, v133
	v_mul_f32_e32 v14, v4, v134
	v_mul_f32_e32 v15, v4, v135
	v_fmac_f32_e32 v8, v7, v129
	v_fmac_f32_e32 v9, v7, v130
	v_fmac_f32_e32 v10, v7, v131
	v_fmac_f32_e32 v11, v7, v132
	v_fmac_f32_e32 v12, v7, v133
	v_fmac_f32_e32 v13, v7, v134
	v_fmac_f32_e32 v14, v7, v135
	v_fmac_f32_e32 v15, v7, v136
	v_fmac_f32_e32 v8, v6, v130
	v_fmac_f32_e32 v9, v6, v131
; __device__ __forceinline__ unsigned pk2(float lo, float hi) { unsigned r; asm("v_cvt_pk_bf16_f32 %0, %1, %2" : "=v"(r) : "v"(lo), "v"(hi)); return r; }
; __device__ __forceinline__ float bf2f(bf16_t b) { return __uint_as_float(((unsigned)b) << 16); }
; __device__ __forceinline__ float bflo(unsigned w) { return __uint_as_float(w << 16); }
; __device__ __forceinline__ float bfhi(unsigned w) { return __uint_as_float(w & 0xffff0000u); }
; __device__ __forceinline__ void hyena_unit(const Args& a, int L, int c, LAS unsigned char* lds) {
;     ...
;             float x[10];
;             x[0] = (s == 0) ? 0.f : bf2f(src[t0 - 1]);
;             x[1] = bflo(v.x); x[2] = bfhi(v.x); x[3] = bflo(v.y); x[4] = bfhi(v.y); x[5] = bflo(v.z); x[6] = bfhi(v.z); x[7] = bflo(v.w); x[8] = bfhi(v.w);
;             x[9] = (s == 2040) ? 0.f : bf2f(src[t0 + 8]);
;             float y[8];
; #pragma unroll
;             for (int j = 0; j < 8; ++j) y[j] = w0 * x[j] + w1 * x[j + 1] + w2 * x[j + 2] + bb;
;             u32x4 o; o.x = pk2(y[0], y[1]); o.y = pk2(y[2], y[3]); o.z = pk2(y[4], y[5]); o.w = pk2(y[6], y[7]);
;             *(u32x4*)(dst + t0) = o;
	v_fmac_f32_e32 v10, v6, v132
	v_fmac_f32_e32 v11, v6, v133
	v_fmac_f32_e32 v12, v6, v134
	v_fmac_f32_e32 v13, v6, v135
	v_fmac_f32_e32 v14, v6, v136
	v_fmac_f32_e32 v15, v6, v137
	v_add_f32_e32 v8, v18, v8
	v_add_f32_e32 v9, v18, v9
	v_add_f32_e32 v10, v18, v10
	v_add_f32_e32 v11, v18, v11
	v_add_f32_e32 v12, v18, v12
	v_add_f32_e32 v13, v18, v13
	v_add_f32_e32 v14, v18, v14
	v_add_f32_e32 v15, v18, v15
	v_cvt_pk_bf16_f32 v84, v8, v9
	v_cvt_pk_bf16_f32 v85, v10, v11
	v_cvt_pk_bf16_f32 v86, v12, v13
	v_cvt_pk_bf16_f32 v87, v14, v15
	global_store_dwordx4 v26, v[84:87], s[24:25]
	s_add_u32 s24, s24, 0x2000
	s_addc_u32 s25, s25, 0
	v_lshlrev_b32_e32 v128, 16, v110
	v_lshlrev_b32_e32 v129, 16, v88
	v_and_b32_e32 v130, 0xffff0000, v88
	v_lshlrev_b32_e32 v131, 16, v89
	v_and_b32_e32 v132, 0xffff0000, v89
	v_lshlrev_b32_e32 v133, 16, v90
	v_and_b32_e32 v134, 0xffff0000, v90
	v_lshlrev_b32_e32 v135, 16, v91
	v_and_b32_e32 v136, 0xffff0000, v91
	v_lshlrev_b32_e32 v137, 16, v126
	v_mul_f32_e32 v8, v4, v128
	v_mul_f32_e32 v9, v4, v129
	v_mul_f32_e32 v10, v4, v130
	v_mul_f32_e32 v11, v4, v131
	v_mul_f32_e32 v12, v4, v132
	v_mul_f32_e32 v13, v4, v133
	v_mul_f32_e32 v14, v4, v134
	v_mul_f32_e32 v15, v4, v135
	v_fmac_f32_e32 v8, v7, v129
	v_fmac_f32_e32 v9, v7, v130
	v_fmac_f32_e32 v10, v7, v131
	v_fmac_f32_e32 v11, v7, v132
	v_fmac_f32_e32 v12, v7, v133
	v_fmac_f32_e32 v13, v7, v134
	v_fmac_f32_e32 v14, v7, v135
	v_fmac_f32_e32 v15, v7, v136
	v_fmac_f32_e32 v8, v6, v130
	v_fmac_f32_e32 v9, v6, v131
	v_fmac_f32_e32 v10, v6, v132
	v_fmac_f32_e32 v11, v6, v133
	v_fmac_f32_e32 v12, v6, v134
	v_fmac_f32_e32 v13, v6, v135
	v_fmac_f32_e32 v14, v6, v136
	v_fmac_f32_e32 v15, v6, v137
	v_add_f32_e32 v8, v18, v8
	v_add_f32_e32 v9, v18, v9
	v_add_f32_e32 v10, v18, v10
	v_add_f32_e32 v11, v18, v11
	v_add_f32_e32 v12, v18, v12
	v_add_f32_e32 v13, v18, v13
	v_add_f32_e32 v14, v18, v14
	v_add_f32_e32 v15, v18, v15
	v_cvt_pk_bf16_f32 v88, v8, v9
	v_cvt_pk_bf16_f32 v89, v10, v11
	v_cvt_pk_bf16_f32 v90, v12, v13
	v_cvt_pk_bf16_f32 v91, v14, v15
	global_store_dwordx4 v26, v[88:91], s[24:25]
	s_add_u32 s24, s24, 0x2000
	s_addc_u32 s25, s25, 0
	v_lshlrev_b32_e32 v128, 16, v111
	v_lshlrev_b32_e32 v129, 16, v92
	v_and_b32_e32 v130, 0xffff0000, v92
	v_lshlrev_b32_e32 v131, 16, v93
	v_and_b32_e32 v132, 0xffff0000, v93
	v_lshlrev_b32_e32 v133, 16, v94
	v_and_b32_e32 v134, 0xffff0000, v94
	v_lshlrev_b32_e32 v135, 16, v95
	v_and_b32_e32 v136, 0xffff0000, v95
	v_lshlrev_b32_e32 v137, 16, v127
	v_mul_f32_e32 v8, v4, v128
	v_mul_f32_e32 v9, v4, v129
	v_mul_f32_e32 v10, v4, v130
	v_mul_f32_e32 v11, v4, v131
	v_mul_f32_e32 v12, v4, v132
	v_mul_f32_e32 v13, v4, v133
	v_mul_f32_e32 v14, v4, v134
	v_mul_f32_e32 v15, v4, v135
	v_fmac_f32_e32 v8, v7, v129
	v_fmac_f32_e32 v9, v7, v130
	v_fmac_f32_e32 v10, v7, v131
	v_fmac_f32_e32 v11, v7, v132
	v_fmac_f32_e32 v12, v7, v133
	v_fmac_f32_e32 v13, v7, v134
	v_fmac_f32_e32 v14, v7, v135
	v_fmac_f32_e32 v15, v7, v136
	v_fmac_f32_e32 v8, v6, v130
	v_fmac_f32_e32 v9, v6, v131
	v_fmac_f32_e32 v10, v6, v132
	v_fmac_f32_e32 v11, v6, v133
	v_fmac_f32_e32 v12, v6, v134
	v_fmac_f32_e32 v13, v6, v135
	v_fmac_f32_e32 v14, v6, v136
	v_fmac_f32_e32 v15, v6, v137
	v_add_f32_e32 v8, v18, v8
	v_add_f32_e32 v9, v18, v9
	v_add_f32_e32 v10, v18, v10
	v_add_f32_e32 v11, v18, v11
	v_add_f32_e32 v12, v18, v12
	v_add_f32_e32 v13, v18, v13
	v_add_f32_e32 v14, v18, v14
	v_add_f32_e32 v15, v18, v15
	v_cvt_pk_bf16_f32 v92, v8, v9
	v_cvt_pk_bf16_f32 v93, v10, v11
	v_cvt_pk_bf16_f32 v94, v12, v13
	v_cvt_pk_bf16_f32 v95, v14, v15
	global_store_dwordx4 v26, v[92:95], s[24:25]
	s_branch .LBB0_162
